# gla_a/gla_c: hoist wdec1+bias loads to unit top (one round trip), gn-gain loads hoisted out of gla_c unit loop, 4th og-gate load issued early
# speedup vs baseline: 1.0116x; 1.0056x over previous
.LBB0_651:
	s_lshl_b32 s0, s28, 6
	s_add_i32 s43, s13, s0
	v_add_u32_e32 v6, s43, v128
	v_mov_b64_e32 v[0:1], s[20:21]
	v_mad_i64_i32 v[2:3], s[0:1], v6, s37, v[0:1]
	v_lshl_add_u64 v[2:3], v[2:3], 0, v[30:31]
	v_add_u32_e32 v4, 16, v6
	v_add_co_u32_e32 v2, vcc, 0x1000, v2
	v_mad_i64_i32 v[4:5], s[0:1], v4, s37, v[0:1]
	s_nop 0
	v_addc_co_u32_e32 v3, vcc, 0, v3, vcc
	v_lshl_add_u64 v[4:5], v[4:5], 0, v[30:31]
	v_add_co_u32_e32 v4, vcc, 0x1000, v4
	s_and_b32 s44, s12, 3
	s_nop 0
	v_addc_co_u32_e32 v5, vcc, 0, v5, vcc
	global_load_dwordx4 v[16:19], v[2:3], off offset:1344
	global_load_dwordx4 v[12:15], v[4:5], off offset:1344
	v_add_u32_e32 v2, 32, v6
	v_mad_i64_i32 v[2:3], s[0:1], v2, s37, v[0:1]
	v_lshl_add_u64 v[2:3], v[2:3], 0, v[30:31]
	v_add_u32_e32 v4, 48, v6
	v_add_co_u32_e32 v2, vcc, 0x1000, v2
	v_mad_i64_i32 v[0:1], s[0:1], v4, s37, v[0:1]
	s_nop 0
	v_addc_co_u32_e32 v3, vcc, 0, v3, vcc
	v_lshl_add_u64 v[0:1], v[0:1], 0, v[30:31]
	v_add_co_u32_e32 v0, vcc, 0x1000, v0
	s_lshl_b32 s22, s44, 9
	s_nop 0
	v_addc_co_u32_e32 v1, vcc, 0, v1, vcc
	global_load_dwordx4 v[8:11], v[2:3], off offset:1344
	s_nop 0
	global_load_dwordx4 v[0:3], v[0:1], off offset:1344
	v_lshl_add_u64 v[24:25], v[32:33], 0, s[22:23]
	v_mov_b32_e32 v4, 0
	v_lshlrev_b32_e32 v26, 2, v34
	v_mov_b32_e32 v20, 0
	s_waitcnt lgkmcnt(0)
	v_mov_b32_e32 v21, 0
	v_mov_b32_e32 v22, 0
	v_mov_b32_e32 v23, 0
	s_lshl_b32 s98, s44, 7
	s_or_b32 s98, s98, s34
	v_or_b32_e32 v208, s98, v34
	v_mov_b32_e32 v209, v31
	v_lshl_add_u64 v[208:209], v[208:209], 2, s[90:91]
	global_load_dword v210, v[208:209], off
	global_load_dword v211, v[208:209], off offset:64
	s_and_saveexec_b64 s[0:1], s[2:3]
	s_cbranch_execz .LBB0_653
	v_mov_b32_e32 v27, v31
	v_lshl_add_u64 v[6:7], v[24:25], 0, v[26:27]
	v_add_co_u32_e32 v20, vcc, 0x1000, v6
	s_nop 1
	v_addc_co_u32_e32 v21, vcc, 0, v7, vcc
	v_add_co_u32_e32 v22, vcc, 0x2000, v6
	s_nop 1
	v_addc_co_u32_e32 v23, vcc, 0, v7, vcc
	v_add_co_u32_e32 v28, vcc, 0x3000, v6
	s_nop 1
	v_addc_co_u32_e32 v29, vcc, 0, v7, vcc
	global_load_dword v200, v[6:7], off offset:64
	global_load_dword v201, v[6:7], off offset:2112
	global_load_dword v202, v[20:21], off offset:64
	global_load_dword v203, v[20:21], off offset:2112
	global_load_dword v204, v[22:23], off offset:64
	global_load_dword v205, v[22:23], off offset:2112
	global_load_dword v206, v[28:29], off offset:64
	global_load_dword v207, v[28:29], off offset:2112
	global_load_dword v5, v[6:7], off
	s_nop 0
	global_load_dword v6, v[6:7], off offset:2048
	s_nop 0
	global_load_dword v7, v[20:21], off
	s_nop 0
	global_load_dword v21, v[20:21], off offset:2048
	s_nop 0
	global_load_dword v27, v[22:23], off
	s_nop 0
	global_load_dword v22, v[22:23], off offset:2048
	s_nop 0
	global_load_dword v23, v[28:29], off
	s_nop 0
	global_load_dword v28, v[28:29], off offset:2048
	s_waitcnt vmcnt(0)
	v_cvt_pk_bf16_f32 v20, v5, v6
	v_cvt_pk_bf16_f32 v21, v7, v21
	v_cvt_pk_bf16_f32 v22, v27, v22
	v_cvt_pk_bf16_f32 v23, v23, v28
.LBB0_653:
	s_or_b64 exec, exec, s[0:1]
	s_lshl_b32 s22, s44, 7
	s_or_b32 s45, s22, s34
	s_waitcnt vmcnt(0)
	v_mov_b32_e32 v5, v210
	v_mfma_f32_16x16x32_bf16 v[42:45], v[16:19], v[20:23], 0
	v_add_u32_e32 v28, 0x400, v126
	v_mfma_f32_16x16x32_bf16 v[46:49], v[12:15], v[20:23], 0
	s_nop 5
	v_add_f32_e32 v6, v5, v42
	v_add_f32_e32 v7, v5, v43
	v_min_f32_e32 v43, 0, v6
	v_mul_f32_e64 v6, |v6|, s38
	v_add_f32_e32 v27, v5, v44
	v_min_f32_e32 v44, 0, v7
	v_mul_f32_e64 v7, |v7|, s38
	v_exp_f32_e32 v6, v6
	v_add_f32_e32 v29, v5, v45
	v_min_f32_e32 v45, 0, v27
	v_mul_f32_e64 v27, |v27|, s38
	v_exp_f32_e32 v7, v7
	v_add_f32_e32 v41, v5, v46
	v_min_f32_e32 v46, 0, v29
	v_mul_f32_e64 v29, |v29|, s38
	v_exp_f32_e32 v27, v27
	v_exp_f32_e32 v29, v29
	v_add_f32_e32 v6, 1.0, v6
	v_add_f32_e32 v7, 1.0, v7
	v_add_f32_e32 v42, v5, v47
	v_min_f32_e32 v47, 0, v41
	v_mul_f32_e64 v41, |v41|, s38
	v_add_f32_e32 v27, 1.0, v27
	v_exp_f32_e32 v41, v41
	v_add_f32_e32 v29, 1.0, v29
	v_log_f32_e32 v6, v6
	v_log_f32_e32 v7, v7
	v_log_f32_e32 v27, v27
	v_add_f32_e32 v41, 1.0, v41
	v_log_f32_e32 v29, v29
	v_cmp_gt_f32_e64 s[16:17], s39, v41
	v_cndmask_b32_e64 v55, 0, 32, s[16:17]
	v_ldexp_f32 v41, v41, v55
	v_log_f32_e32 v41, v41
	v_mul_f32_e64 v50, |v42|, s38
	v_exp_f32_e32 v50, v50
	v_mul_f32_e32 v60, 0x3f317217, v41
	v_fma_f32 v60, v41, s40, -v60
	v_fma_f32 v6, -v6, s40, v43
	v_fma_f32 v7, -v7, s40, v44
	v_fmac_f32_e32 v60, 0x3377d1cf, v41
	v_fma_f32 v27, -v27, s40, v45
	v_fma_f32 v29, -v29, s40, v46
	v_mul_f32_e32 v6, 0x3d800000, v6
	v_mul_f32_e32 v7, 0x3d800000, v7
	v_fmac_f32_e32 v60, 0x3f317217, v41
	v_cmp_lt_f32_e64 vcc, |v41|, s41
	v_mul_f32_e32 v27, 0x3d800000, v27
	v_mul_f32_e32 v29, 0x3d800000, v29
	ds_write2_b32 v126, v6, v7 offset1:129
	ds_write2_b32 v28, v27, v29 offset0:2 offset1:131
	v_add_f32_e32 v7, 1.0, v50
	v_cndmask_b32_e32 v41, v41, v60, vcc
	v_cndmask_b32_e64 v55, 0, v125, s[16:17]
	v_sub_f32_e32 v6, v41, v55
	v_log_f32_e32 v7, v7
	v_add_f32_e32 v41, v5, v48
	v_min_f32_e32 v27, 0, v42
	v_mul_f32_e64 v42, |v41|, s38
	v_exp_f32_e32 v42, v42
	v_sub_f32_e32 v6, v47, v6
	v_mul_f32_e32 v6, 0x3d800000, v6
	v_fma_f32 v7, -v7, s40, v27
	v_add_f32_e32 v27, 1.0, v42
	v_cmp_gt_f32_e32 vcc, s39, v27
	v_mul_f32_e32 v7, 0x3d800000, v7
	s_nop 0
	v_cndmask_b32_e64 v29, 0, 32, vcc
	v_ldexp_f32 v27, v27, v29
	v_log_f32_e32 v27, v27
	v_add_u32_e32 v29, 0x2000, v126
	ds_write2_b32 v29, v6, v7 offset0:16 offset1:145
	v_min_f32_e32 v6, 0, v41
	v_add_f32_e32 v41, v5, v49
	v_mul_f32_e32 v7, 0x3f317217, v27
	v_mul_f32_e64 v42, |v41|, s38
	v_fma_f32 v7, v27, s40, -v7
	v_exp_f32_e32 v42, v42
	v_fmac_f32_e32 v7, 0x3377d1cf, v27
	v_fmac_f32_e32 v7, 0x3f317217, v27
	v_cmp_lt_f32_e64 s[0:1], |v27|, s41
	s_nop 1
	v_cndmask_b32_e64 v7, v27, v7, s[0:1]
	v_cndmask_b32_e32 v27, 0, v125, vcc
	v_sub_f32_e32 v7, v7, v27
	v_add_f32_e32 v27, 1.0, v42
	v_sub_f32_e32 v6, v6, v7
	v_min_f32_e32 v7, 0, v41
	v_log_f32_e32 v27, v27
	v_mfma_f32_16x16x32_bf16 v[42:45], v[8:11], v[20:23], 0
	v_mul_f32_e32 v6, 0x3d800000, v6
	s_nop 3
	s_nop 2
	v_add_f32_e32 v42, v5, v42
	v_mul_f32_e64 v46, |v42|, s38
	v_exp_f32_e32 v46, v46
	v_mfma_f32_16x16x32_bf16 v[20:23], v[0:3], v[20:23], 0
	s_nop 0
	v_fma_f32 v7, -v27, s40, v7
	v_add_f32_e32 v27, 1.0, v46
	v_cmp_gt_f32_e32 vcc, s39, v27
	v_mul_f32_e32 v7, 0x3d800000, v7
	s_nop 2
	v_add_f32_e32 v21, v5, v21
	v_cndmask_b32_e64 v41, 0, 32, vcc
	v_ldexp_f32 v27, v27, v41
	v_log_f32_e32 v27, v27
	v_add_u32_e32 v41, 0x2400, v126
	ds_write2_b32 v41, v6, v7 offset0:18 offset1:147
	v_min_f32_e32 v6, 0, v42
	v_add_f32_e32 v42, v5, v43
	v_mul_f32_e32 v7, 0x3f317217, v27
	v_mul_f32_e64 v43, |v42|, s38
	v_fma_f32 v7, v27, s40, -v7
	v_exp_f32_e32 v43, v43
	v_fmac_f32_e32 v7, 0x3377d1cf, v27
	v_fmac_f32_e32 v7, 0x3f317217, v27
	v_cmp_lt_f32_e64 s[0:1], |v27|, s41
	v_add_f32_e32 v22, v5, v22
	s_nop 0
	v_cndmask_b32_e64 v7, v27, v7, s[0:1]
	v_cndmask_b32_e32 v27, 0, v125, vcc
	v_sub_f32_e32 v7, v7, v27
	v_add_f32_e32 v27, 1.0, v43
	v_sub_f32_e32 v6, v6, v7
	v_min_f32_e32 v7, 0, v42
	v_log_f32_e32 v27, v27
	v_add_f32_e32 v43, v5, v44
	v_mul_f32_e64 v44, |v43|, s38
	v_exp_f32_e32 v44, v44
	v_mul_f32_e32 v6, 0x3d800000, v6
	s_nop 0
	v_fma_f32 v7, -v27, s40, v7
	v_add_f32_e32 v27, 1.0, v44
	v_cmp_gt_f32_e32 vcc, s39, v27
	v_mul_f32_e32 v7, 0x3d800000, v7
	s_nop 0
	v_cndmask_b32_e64 v42, 0, 32, vcc
	v_ldexp_f32 v27, v27, v42
	v_log_f32_e32 v27, v27
	v_add_u32_e32 v42, 0x4000, v126
	ds_write2_b32 v42, v6, v7 offset0:32 offset1:161
	v_min_f32_e32 v6, 0, v43
	v_add_f32_e32 v43, v5, v45
	v_mul_f32_e32 v7, 0x3f317217, v27
	v_mul_f32_e64 v44, |v43|, s38
	v_fma_f32 v7, v27, s40, -v7
	v_exp_f32_e32 v44, v44
	v_fmac_f32_e32 v7, 0x3377d1cf, v27
	v_fmac_f32_e32 v7, 0x3f317217, v27
	v_cmp_lt_f32_e64 s[0:1], |v27|, s41
	s_nop 1
	v_cndmask_b32_e64 v7, v27, v7, s[0:1]
	v_cndmask_b32_e32 v27, 0, v125, vcc
	v_sub_f32_e32 v7, v7, v27
	v_add_f32_e32 v27, 1.0, v44
	v_sub_f32_e32 v6, v6, v7
	v_min_f32_e32 v7, 0, v43
	v_log_f32_e32 v27, v27
	v_add_f32_e32 v44, v5, v20
	v_mul_f32_e64 v20, |v44|, s38
	v_exp_f32_e32 v20, v20
	s_nop 0
	v_add_f32_e32 v20, 1.0, v20
	v_mul_f32_e32 v6, 0x3d800000, v6
	v_cmp_gt_f32_e32 vcc, s39, v20
	v_fma_f32 v7, -v27, s40, v7
	v_mul_f32_e32 v7, 0x3d800000, v7
	v_cndmask_b32_e64 v27, 0, 32, vcc
	v_ldexp_f32 v20, v20, v27
	v_log_f32_e32 v27, v20
	v_add_u32_e32 v20, 0x4400, v126
	ds_write2_b32 v20, v6, v7 offset0:34 offset1:163
	v_mul_f32_e64 v43, |v21|, s38
	v_mul_f32_e32 v7, 0x3f317217, v27
	v_fma_f32 v7, v27, s40, -v7
	v_exp_f32_e32 v43, v43
	v_fmac_f32_e32 v7, 0x3377d1cf, v27
	v_fmac_f32_e32 v7, 0x3f317217, v27
	v_cmp_lt_f32_e64 s[0:1], |v27|, s41
	v_min_f32_e32 v6, 0, v44
	v_add_f32_e32 v5, v5, v23
	v_cndmask_b32_e64 v7, v27, v7, s[0:1]
	v_cndmask_b32_e32 v27, 0, v125, vcc
	v_sub_f32_e32 v7, v7, v27
	v_add_f32_e32 v27, 1.0, v43
	v_sub_f32_e32 v6, v6, v7
	v_min_f32_e32 v7, 0, v21
	v_log_f32_e32 v27, v27
	v_mul_f32_e64 v43, |v22|, s38
	v_exp_f32_e32 v43, v43
	v_mul_f32_e32 v6, 0x3d800000, v6
	s_nop 1
	v_fma_f32 v7, -v27, s40, v7
	v_add_f32_e32 v21, 1.0, v43
	v_mul_f32_e32 v7, 0x3d800000, v7
	s_nop 0
	v_log_f32_e32 v27, v21
	v_add_u32_e32 v21, 0x6000, v126
	ds_write2_b32 v21, v6, v7 offset0:48 offset1:177
	v_min_f32_e32 v6, 0, v22
	v_mul_f32_e64 v22, |v5|, s38
	v_exp_f32_e32 v22, v22
	s_nop 0
	v_add_f32_e32 v22, 1.0, v22
	v_fma_f32 v6, -v27, s40, v6
	v_log_f32_e32 v22, v22
	v_min_f32_e32 v5, 0, v5
	v_mul_f32_e32 v6, 0x3d800000, v6
	s_nop 1
	v_fma_f32 v5, -v22, s40, v5
	v_mul_f32_e32 v5, 0x3d800000, v5
	v_add_u32_e32 v22, 0x6400, v126
	ds_write2_b32 v22, v6, v5 offset0:50 offset1:179
	v_mov_b32_e32 v5, 0
	v_mov_b32_e32 v6, 0
	v_mov_b32_e32 v7, 0
	s_and_saveexec_b64 s[0:1], s[2:3]
	s_cbranch_execz .LBB0_655
	v_cvt_pk_bf16_f32 v4, v200, v201
	v_cvt_pk_bf16_f32 v5, v202, v203
	v_cvt_pk_bf16_f32 v6, v204, v205
	v_cvt_pk_bf16_f32 v7, v206, v207
.LBB0_655:
	s_or_b64 exec, exec, s[0:1]
	v_add_u32_e32 v24, s45, v34
	v_mov_b32_e32 v25, v31
	v_lshl_add_u64 v[24:25], v[24:25], 2, s[90:91]
	v_mov_b32_e32 v23, v211
	v_mfma_f32_16x16x32_bf16 v[16:19], v[16:19], v[4:7], 0
	v_add_u32_e32 v129, 0x800, v127
	v_add_u32_e32 v130, 0xc00, v127
	v_add_u32_e32 v132, 0x1000, v127
	v_mfma_f32_16x16x32_bf16 v[12:15], v[12:15], v[4:7], 0
	v_add_u32_e32 v135, 0x1400, v127
	v_add_u32_e32 v138, 0x1800, v127
	v_add_u32_e32 v133, 0x1c00, v127
	v_mfma_f32_16x16x32_bf16 v[8:11], v[8:11], v[4:7], 0
	v_add_u32_e32 v136, 0x2000, v127
	v_add_u32_e32 v139, 0x2400, v127
	v_add_u32_e32 v141, 0x2800, v127
	v_mfma_f32_16x16x32_bf16 v[0:3], v[0:3], v[4:7], 0
	v_add_u32_e32 v142, 0x2c00, v127
	v_add_u32_e32 v140, 0x3000, v127
	v_add_u32_e32 v137, 0x3400, v127
	v_add_u32_e32 v134, 0x3800, v127
	v_add_u32_e32 v131, 0x3c00, v127
	s_waitcnt vmcnt(0)
	s_add_i32 s98, s30, s72
	s_cmpk_lt_i32 s98, 0x880
	s_cbranch_scc0 .Lpf_a_skip
	s_cmpk_gt_i32 s98, 0x7ff
	s_cbranch_scc1 .Lpf_a_ctx
	s_lshr_b32 s99, s98, 8
	s_bfe_u32 s100, s98, 0x20006
	s_and_b32 s101, s98, 63
	s_lshl_b32 s99, s99, 12
	s_branch .Lpf_a_go

.LBB0_816:
	s_cmp_lt_i32 s56, 6
	s_cselect_b64 s[2:3], -1, 0
	s_and_b64 s[66:67], s[2:3], s[0:1]
	s_andn2_b64 vcc, exec, s[66:67]
	s_cbranch_vccnz .LBB0_856
	s_cmpk_lt_i32 s33, 0x800
	v_and_b32_e32 v84, 15, v145
	v_lshrrev_b32_e32 v35, 7, v145
	v_lshrrev_b32_e32 v85, 3, v145
	s_cbranch_scc0 .LBB0_832
	s_add_u32 s68, s54, 0x6800000
	s_waitcnt lgkmcnt(0)
	v_lshrrev_b32_e32 v1, 4, v144
	v_readlane_b32 s45, v244, 6
	s_addc_u32 s69, s55, 0
	v_lshlrev_b32_e32 v0, 3, v1
	s_lshr_b32 s0, s45, 8
	v_readlane_b32 s44, v244, 25
	v_lshrrev_b32_e32 v2, 5, v144
	s_lshl_b32 s1, s44, 5
	v_cmp_eq_u32_e64 s[2:3], s0, v2
	v_lshlrev_b32_e32 v1, 2, v1
	v_and_b32_e32 v2, 8, v0
	v_mov_b32_e32 v31, 0
	s_lshl_b32 s78, s0, 9
	v_lshl_or_b32 v4, s0, 6, v1
	v_lshl_or_b32 v30, s0, 4, v2
	s_and_b32 s0, s1, 0x60
	v_lshlrev_b64 v[2:3], 11, v[30:31]
	v_or_b32_e32 v34, s0, v84
	s_movk_i32 s0, 0x204
	v_lshl_add_u64 v[32:33], s[88:89], 0, v[2:3]
	v_mul_lo_u32 v7, v4, s0
	v_and_b32_e32 v2, 0x7f, v145
	v_and_b32_e32 v4, 1, v35
	v_mul_u32_u24_e32 v6, 0x8100, v4
	v_lshlrev_b32_e32 v2, 2, v2
	v_add3_u32 v8, 0, v6, v2
	v_cmp_eq_u32_e64 s[4:5], 0, v4
	v_cmp_eq_u32_e64 s[6:7], 1, v4
	v_and_b32_e32 v6, 0x300, v145
	v_lshlrev_b32_e32 v4, 7, v4
	v_sub_u32_e32 v4, v4, v6
	v_lshlrev_b32_e32 v4, 2, v4
	s_add_i32 s8, 0, 0x10600
	s_add_i32 s12, 0, 0x10200
	v_lshrrev_b32_e32 v5, 8, v145
	v_add3_u32 v88, s8, v4, v2
	v_lshl_add_u32 v89, v145, 2, s12
	v_and_b32_e32 v2, 0x78, v85
	v_mad_u32_u24 v4, v144, s0, 0
	v_or_b32_e32 v6, 7, v85
	s_lshl_b32 s12, s44, 3
	v_mul_u32_u24_e32 v9, 0x4080, v5
	v_cmp_eq_u32_e64 s[8:9], 1, v5
	v_mul_u32_u24_e32 v5, 0x110, v144
	s_add_i32 s42, 0, 0x12800
	v_lshl_add_u32 v90, v2, 2, v4
	v_lshl_add_u32 v91, v6, 2, v4
	v_lshlrev_b32_e32 v4, 1, v2
	s_and_b32 s12, s12, 0x1ffffff0
	s_movk_i32 s0, 0x110
	v_add3_u32 v92, s42, v5, v4
	v_or_b32_e32 v4, s12, v84
	v_mul_lo_u32 v4, v4, s0
	v_and_b32_e32 v5, 48, v144
	s_add_i32 s13, s12, 0x80
	v_add3_u32 v93, s42, v4, v5
	v_or_b32_e32 v4, s13, v84
	v_mul_lo_u32 v4, v4, s0
	v_mul_u32_u24_e32 v12, 0x90, v6
	v_add3_u32 v94, s42, v4, v5
	v_or_b32_e32 v4, s12, v1
	v_and_or_b32 v6, s1, 32, v84
	v_mul_u32_u24_e32 v13, 0x110, v6
	v_or_b32_e32 v15, 1, v4
	v_or_b32_e32 v16, 2, v4
	v_or_b32_e32 v17, 3, v4
	s_bfe_u32 s0, s45, 0x20006
	s_lshl_b32 s1, s44, 4
	s_movk_i32 s43, 0x90
	v_add3_u32 v95, s42, v13, v5
	v_lshl_add_u32 v13, v6, 1, 0
	v_cmp_gt_u32_e64 s[12:13], v6, v4
	v_cmp_lt_u32_e64 s[14:15], v6, v4
	v_cmp_gt_u32_e64 s[16:17], v6, v15
	v_cmp_gt_u32_e64 s[18:19], v6, v16
	v_cmp_lt_u32_e64 s[20:21], v6, v16
	v_cmp_gt_u32_e64 s[22:23], v6, v17
	v_cmp_lt_u32_e64 s[24:25], v6, v17
	v_or_b32_e32 v6, 16, v6
	v_lshl_or_b32 v97, s0, 4, v84
	s_and_b32 s44, s1, 0x3fffffc0
	v_mul_lo_u32 v14, v4, s43
	v_cmp_gt_u32_e64 s[26:27], v6, v4
	v_cmp_lt_u32_e64 s[28:29], v6, v4
	v_mul_u32_u24_e32 v4, 0x110, v97
	v_or_b32_e32 v30, s44, v84
	v_add3_u32 v98, s42, v4, v5
	v_or_b32_e32 v4, 16, v30
	v_mov_b32_e32 v5, v31
	v_cmp_gt_u32_e64 s[30:31], v6, v15
	v_cmp_gt_u32_e64 s[34:35], v6, v16
	v_cmp_lt_u32_e64 s[36:37], v6, v16
	v_cmp_gt_u32_e64 s[38:39], v6, v17
	v_cmp_lt_u32_e64 s[40:41], v6, v17
	v_lshlrev_b64 v[38:39], 8, v[4:5]
	v_or_b32_e32 v4, s44, v1
	v_or3_b32 v6, v1, s1, 48
	v_mbcnt_lo_u32_b32 v1, -1, 0
	v_mbcnt_hi_u32_b32 v1, -1, v1
	v_and_b32_e32 v20, 64, v1
	v_xor_b32_e32 v19, 16, v1
	v_add_u32_e32 v20, 64, v20
	v_cmp_lt_i32_e32 vcc, v19, v20
	v_mul_lo_u32 v18, v30, s43
	v_lshlrev_b64 v[36:37], 8, v[30:31]
	v_or_b32_e32 v30, 32, v30
	s_lshl_b32 s0, s0, 6
	v_cndmask_b32_e32 v19, v1, v19, vcc
	v_lshlrev_b64 v[40:41], 8, v[30:31]
	v_or3_b32 v30, v144, s1, 48
	s_and_b32 s45, s45, 0xffffff00
	s_add_i32 s0, s0, 0
	v_lshlrev_b32_e32 v101, 2, v19
	v_xor_b32_e32 v19, 32, v1
	v_and_b32_e32 v16, 48, v145
	v_mul_lo_u32 v5, v30, s43
	v_lshlrev_b64 v[42:43], 8, v[30:31]
	s_add_i32 s45, s0, s45
	v_lshlrev_b32_e32 v30, 2, v4
	v_cmp_lt_i32_e32 vcc, v19, v20
	v_lshl_add_u32 v3, v34, 2, 0
	s_movk_i32 s10, 0x100
	v_lshl_add_u32 v10, v144, 1, 0
	v_mul_u32_u24_e32 v11, 0x90, v2
	v_mad_u32_u24 v15, v97, s43, 0
	v_add_u32_e32 v17, 0, v16
	s_add_u32 s72, s54, 0x4400000
	v_lshl_add_u64 v[44:45], s[92:93], 0, v[30:31]
	v_lshlrev_b32_e32 v30, 2, v6
	v_cndmask_b32_e32 v1, v1, v19, vcc
	s_mov_b32 s71, 0
	v_or_b32_e32 v86, 0x80, v145
	v_and_b32_e32 v87, 0x37f, v145
	v_cmp_gt_u32_e64 s[10:11], s10, v145
	v_add_u32_e32 v96, 0x1100, v95
	v_cmp_gt_u32_e64 s[42:43], 16, v144
	v_lshl_add_u32 v99, v144, 2, s45
	v_lshl_add_u32 v100, v84, 2, s0
	s_addc_u32 s73, s55, 0
	v_lshl_add_u64 v[46:47], s[92:93], 0, v[30:31]
	v_lshlrev_b32_e32 v102, 2, v1
	s_movk_i32 s79, 0x2600
	s_mov_b32 s80, 0xbfb8aa3b
	s_mov_b32 s81, 0x800000
	s_mov_b32 s82, 0x3f317217
	s_mov_b32 s83, 0x7f800000
	v_lshlrev_b32_e32 v48, 1, v2
	s_mov_b32 s74, 0x3db504f3
	v_add_u32_e32 v103, v10, v11
	v_add_u32_e32 v104, v10, v12
	v_add_u32_e32 v105, v13, v14
	v_add_u32_e32 v106, v15, v16
	v_lshlrev_b32_e32 v30, 1, v0
	v_add_u32_e32 v107, v17, v18
	v_add_u32_e32 v108, v17, v5
	v_mov_b32_e32 v109, 0x358637bd
	s_mov_b64 s[76:77], 0x1140
	v_lshlrev_b32_e32 v50, 1, v4
	v_lshlrev_b32_e32 v52, 1, v6
	v_mov_b32_e32 v110, 0x41b17218
	v_add_u32_e32 v111, v3, v7
	v_add_u32_e32 v112, v8, v9
	s_mov_b32 s84, s33
	global_load_dwordx4 v[212:215], v[44:45], off
	global_load_dwordx4 v[216:219], v[44:45], off offset:64
	global_load_dwordx4 v[220:223], v[44:45], off offset:128
	global_load_dwordx4 v[224:227], v[46:47], off
	s_waitcnt vmcnt(0)
	s_branch .LBB0_820
.LBB0_819:
	s_or_b64 exec, exec, s[0:1]
	v_or_b32_e32 v16, s44, v97
	v_mov_b64_e32 v[18:19], s[68:69]
	v_mad_i64_i32 v[18:19], s[0:1], v16, s79, v[18:19]
	v_lshl_add_u64 v[18:19], v[18:19], 0, s[70:71]
	v_lshl_add_u64 v[20:21], v[18:19], 0, s[76:77]
	v_mov_b32_e32 v230, v52
	v_mov_b32_e32 v231, v31
	v_lshl_add_u64 v[230:231], v[20:21], 0, v[230:231]
	v_mov_b32_e32 v51, v31
	v_lshl_add_u64 v[24:25], v[20:21], 0, v[50:51]
	s_waitcnt lgkmcnt(0)
	s_barrier
	global_load_dwordx2 v[54:55], v[24:25], off
	ds_read2st64_b32 v[18:19], v100 offset0:108 offset1:109
	v_ashrrev_i32_e32 v17, 31, v16
	v_lshlrev_b64 v[16:17], 10, v[16:17]
	v_lshl_add_u64 v[16:17], s[72:73], 0, v[16:17]
	v_lshl_add_u64 v[16:17], v[16:17], 0, s[70:71]
	s_waitcnt lgkmcnt(0)
	v_add_f32_e32 v18, v18, v19
	v_fmamk_f32 v18, v18, 0x3c000000, v109
	v_rsq_f32_e32 v18, v18
	v_lshl_add_u64 v[22:23], v[16:17], 0, v[50:51]
	global_load_dwordx2 v[56:57], v[24:25], off offset:32
	s_nop 0
	global_load_dwordx2 v[24:25], v[24:25], off offset:64
	global_load_dwordx2 v[228:229], v[230:231], off
	v_pk_mul_f32 v[12:13], v[12:13], v[18:19] op_sel_hi:[1,0]
	v_pk_mul_f32 v[14:15], v[14:15], v[18:19] op_sel_hi:[1,0]
	s_waitcnt vmcnt(3)
	v_lshlrev_b32_e32 v58, 16, v54
	v_and_b32_e32 v59, 0xffff0000, v54
	v_mul_f32_e32 v19, 0xbfb8aa3b, v58
	v_mul_f32_e32 v49, 0xbfb8aa3b, v59
	v_lshlrev_b32_e32 v54, 16, v55
	v_and_b32_e32 v55, 0xffff0000, v55
	v_exp_f32_e32 v60, v19
	v_exp_f32_e32 v61, v49
	v_mul_f32_e32 v51, 0xbfb8aa3b, v54
	v_mul_f32_e32 v53, 0xbfb8aa3b, v55
	v_exp_f32_e32 v62, v51
	v_exp_f32_e32 v63, v53
	v_pk_mul_f32 v[12:13], v[212:213], v[12:13]
	v_pk_add_f32 v[26:27], v[60:61], 1.0 op_sel_hi:[1,0]
	v_pk_mul_f32 v[14:15], v[214:215], v[14:15]
	v_pk_add_f32 v[28:29], v[62:63], 1.0 op_sel_hi:[1,0]
	s_mov_b64 vcc, s[0:1]
	v_rcp_f32_e32 v27, v27
	s_mov_b64 vcc, s[46:47]
	v_rcp_f32_e32 v26, v26
	s_mov_b64 vcc, s[48:49]
	v_rcp_f32_e32 v29, v29
	v_pk_mul_f32 v[26:27], v[26:27], v[58:59]
	v_rcp_f32_e32 v28, v28
	v_pk_mul_f32 v[12:13], v[12:13], v[26:27]
	v_pk_mul_f32 v[26:27], v[28:29], v[54:55]
	v_cvt_pk_bf16_f32 v12, v12, v13
	v_pk_mul_f32 v[14:15], v[14:15], v[26:27]
	s_waitcnt vmcnt(2)
	v_lshlrev_b32_e32 v26, 16, v56
	v_cvt_pk_bf16_f32 v13, v14, v15
	global_store_dwordx2 v[22:23], v[12:13], off
	v_and_b32_e32 v27, 0xffff0000, v56
	v_mul_f32_e32 v19, 0xbfb8aa3b, v26
	v_mul_f32_e32 v49, 0xbfb8aa3b, v27
	v_lshlrev_b32_e32 v28, 16, v57
	v_and_b32_e32 v29, 0xffff0000, v57
	v_exp_f32_e32 v54, v19
	v_exp_f32_e32 v55, v49
	v_mul_f32_e32 v51, 0xbfb8aa3b, v28
	v_mul_f32_e32 v53, 0xbfb8aa3b, v29
	v_exp_f32_e32 v56, v51
	v_exp_f32_e32 v57, v53
	v_pk_add_f32 v[54:55], v[54:55], 1.0 op_sel_hi:[1,0]
	v_pk_mul_f32 v[8:9], v[8:9], v[18:19] op_sel_hi:[1,0]
	v_pk_mul_f32 v[10:11], v[10:11], v[18:19] op_sel_hi:[1,0]
	v_pk_add_f32 v[56:57], v[56:57], 1.0 op_sel_hi:[1,0]
	s_mov_b64 vcc, s[0:1]
	v_rcp_f32_e32 v55, v55
	s_mov_b64 vcc, s[46:47]
	v_rcp_f32_e32 v54, v54
	s_mov_b64 vcc, s[48:49]
	v_pk_mul_f32 v[26:27], v[54:55], v[26:27]
	v_rcp_f32_e32 v55, v57
	s_nop 0
	v_rcp_f32_e32 v54, v56
	s_nop 0
	v_pk_mul_f32 v[28:29], v[54:55], v[28:29]
	v_mov_b32_e32 v53, v31
	s_waitcnt vmcnt(2)
	v_pk_mul_f32 v[8:9], v[216:217], v[8:9]
	v_pk_mul_f32 v[10:11], v[218:219], v[10:11]
	v_pk_mul_f32 v[8:9], v[8:9], v[26:27]
	v_pk_mul_f32 v[10:11], v[10:11], v[28:29]
	v_cvt_pk_bf16_f32 v8, v8, v9
	v_cvt_pk_bf16_f32 v9, v10, v11
	global_store_dwordx2 v[22:23], v[8:9], off offset:32
	v_lshlrev_b32_e32 v14, 16, v24
	v_and_b32_e32 v15, 0xffff0000, v24
	v_lshl_add_u64 v[12:13], v[20:21], 0, v[52:53]
	v_lshlrev_b32_e32 v20, 16, v25
	v_and_b32_e32 v21, 0xffff0000, v25
	v_mul_f32_e32 v19, 0xbfb8aa3b, v14
	v_mul_f32_e32 v25, 0xbfb8aa3b, v15
	v_exp_f32_e32 v24, v19
	v_exp_f32_e32 v25, v25
	v_mul_f32_e32 v26, 0xbfb8aa3b, v20
	v_mul_f32_e32 v27, 0xbfb8aa3b, v21
	v_exp_f32_e32 v26, v26
	v_exp_f32_e32 v27, v27
	v_pk_add_f32 v[24:25], v[24:25], 1.0 op_sel_hi:[1,0]
	v_pk_mul_f32 v[4:5], v[4:5], v[18:19] op_sel_hi:[1,0]
	v_pk_mul_f32 v[6:7], v[6:7], v[18:19] op_sel_hi:[1,0]
	v_pk_add_f32 v[26:27], v[26:27], 1.0 op_sel_hi:[1,0]
	v_div_scale_f32 v55, s[44:45], v26, v26, 1.0
	v_rcp_f32_e32 v60, v55
	s_nop 0
	v_fma_f32 v64, -v55, v60, 1.0
	v_div_scale_f32 v56, s[48:49], 1.0, v26, 1.0
	v_fmac_f32_e32 v60, v64, v60
	v_mul_f32_e32 v64, v56, v60
	v_fma_f32 v68, -v55, v64, v56
	s_mov_b64 vcc, s[0:1]
	v_fmac_f32_e32 v64, v68, v60
	v_rcp_f32_e32 v25, v25
	s_mov_b64 vcc, s[46:47]
	v_fma_f32 v49, -v55, v64, v56
	v_rcp_f32_e32 v24, v24
	s_mov_b64 vcc, s[48:49]
	v_pk_mul_f32 v[14:15], v[24:25], v[14:15]
	v_rcp_f32_e32 v25, v27
	v_div_fmas_f32 v19, v49, v60, v64
	v_div_fixup_f32 v24, v19, v26, 1.0
	v_pk_mul_f32 v[20:21], v[24:25], v[20:21]
	v_readlane_b32 s0, v244, 4
	v_pk_mul_f32 v[0:1], v[0:1], v[18:19] op_sel_hi:[1,0]
	v_readlane_b32 s1, v244, 5
	s_add_i32 s84, s84, s0
	v_pk_mul_f32 v[2:3], v[2:3], v[18:19] op_sel_hi:[1,0]
	v_pk_mul_f32 v[4:5], v[4:5], v[220:221]
	v_pk_mul_f32 v[6:7], v[6:7], v[222:223]
	v_pk_mul_f32 v[4:5], v[4:5], v[14:15]
	v_pk_mul_f32 v[6:7], v[6:7], v[20:21]
	v_cvt_pk_bf16_f32 v4, v4, v5
	v_cvt_pk_bf16_f32 v5, v6, v7
	global_store_dwordx2 v[22:23], v[4:5], off offset:64
	v_lshl_add_u64 v[10:11], v[16:17], 0, v[52:53]
	s_cmpk_gt_i32 s84, 0x7ff
	s_waitcnt vmcnt(3)
	v_lshlrev_b32_e32 v12, 16, v228
	v_and_b32_e32 v13, 0xffff0000, v228
	v_mul_f32_e32 v14, 0xbfb8aa3b, v12
	v_mul_f32_e32 v15, 0xbfb8aa3b, v13
	v_lshlrev_b32_e32 v8, 16, v229
	v_and_b32_e32 v9, 0xffff0000, v229
	v_exp_f32_e32 v14, v14
	v_exp_f32_e32 v15, v15
	v_mul_f32_e32 v16, 0xbfb8aa3b, v8
	v_mul_f32_e32 v17, 0xbfb8aa3b, v9
	v_exp_f32_e32 v16, v16
	v_exp_f32_e32 v17, v17
	v_pk_mul_f32 v[0:1], v[0:1], v[224:225]
	v_pk_add_f32 v[4:5], v[14:15], 1.0 op_sel_hi:[1,0]
	v_pk_mul_f32 v[2:3], v[2:3], v[226:227]
	v_pk_add_f32 v[6:7], v[16:17], 1.0 op_sel_hi:[1,0]
	s_mov_b64 vcc, s[0:1]
	v_rcp_f32_e32 v5, v5
	s_mov_b64 vcc, s[46:47]
	v_rcp_f32_e32 v4, v4
	s_mov_b64 vcc, s[48:49]
	v_pk_mul_f32 v[4:5], v[4:5], v[12:13]
	v_rcp_f32_e32 v7, v7
	s_nop 0
	v_rcp_f32_e32 v6, v6
	v_pk_mul_f32 v[0:1], v[0:1], v[4:5]
	v_pk_mul_f32 v[4:5], v[6:7], v[8:9]
	v_cvt_pk_bf16_f32 v0, v0, v1
	v_pk_mul_f32 v[2:3], v[2:3], v[4:5]
	s_nop 0
	v_cvt_pk_bf16_f32 v1, v2, v3
	global_store_dwordx2 v[10:11], v[0:1], off
	s_barrier
	s_cbranch_scc1 .LBB0_832
.LBB0_820:
	s_ashr_i32 s85, s84, 8
	s_and_b32 s45, s84, 63
	s_lshl_b32 s0, s85, 12
	s_lshl_b32 s1, s45, 6
	s_or_b32 s44, s0, s1
	v_or_b32_e32 v6, s44, v84
	v_mov_b64_e32 v[0:1], s[68:69]
	v_mad_i64_i32 v[2:3], s[0:1], v6, s79, v[0:1]
	v_lshl_add_u64 v[2:3], v[2:3], 0, v[30:31]
	v_or_b32_e32 v4, 16, v6
	v_add_co_u32_e32 v2, vcc, 0x1000, v2
	v_mad_i64_i32 v[4:5], s[0:1], v4, s79, v[0:1]
	s_nop 0
	v_addc_co_u32_e32 v3, vcc, 0, v3, vcc
	v_lshl_add_u64 v[4:5], v[4:5], 0, v[30:31]
	v_add_co_u32_e32 v4, vcc, 0x1000, v4
	s_bfe_u32 s86, s84, 0x20006
	s_nop 0
	v_addc_co_u32_e32 v5, vcc, 0, v5, vcc
	global_load_dwordx4 v[12:15], v[2:3], off offset:1344
	global_load_dwordx4 v[8:11], v[4:5], off offset:1344
	v_or_b32_e32 v2, 32, v6
	v_mad_i64_i32 v[2:3], s[0:1], v2, s79, v[0:1]
	v_lshl_add_u64 v[2:3], v[2:3], 0, v[30:31]
	v_or_b32_e32 v4, 48, v6
	v_add_co_u32_e32 v2, vcc, 0x1000, v2
	v_mad_i64_i32 v[0:1], s[0:1], v4, s79, v[0:1]
	s_nop 0
	v_addc_co_u32_e32 v3, vcc, 0, v3, vcc
	v_lshl_add_u64 v[0:1], v[0:1], 0, v[30:31]
	v_add_co_u32_e32 v0, vcc, 0x1000, v0
	s_lshl_b32 s70, s86, 9
	s_nop 0
	v_addc_co_u32_e32 v1, vcc, 0, v1, vcc
	global_load_dwordx4 v[4:7], v[2:3], off offset:1344
	s_nop 0
	global_load_dwordx4 v[0:3], v[0:1], off offset:1344
	v_lshl_add_u64 v[20:21], v[32:33], 0, s[70:71]
	v_lshlrev_b32_e32 v22, 2, v34
	v_mov_b32_e32 v16, 0
	v_mov_b32_e32 v17, 0
	v_mov_b32_e32 v18, 0
	v_mov_b32_e32 v19, 0
	s_lshl_b32 s98, s86, 7
	s_or_b32 s98, s98, s78
	v_or_b32_e32 v208, s98, v34
	v_mov_b32_e32 v209, v31
	v_lshl_add_u64 v[208:209], v[208:209], 2, s[90:91]
	global_load_dword v210, v[208:209], off
	global_load_dword v211, v[208:209], off offset:64
	s_and_saveexec_b64 s[0:1], s[2:3]
	s_cbranch_execz .LBB0_822
	v_mov_b32_e32 v23, v31
	v_lshl_add_u64 v[16:17], v[20:21], 0, v[22:23]
	v_add_co_u32_e32 v18, vcc, 0x1000, v16
	s_nop 1
	v_addc_co_u32_e32 v19, vcc, 0, v17, vcc
	v_add_co_u32_e32 v24, vcc, 0x2000, v16
	s_nop 1
	v_addc_co_u32_e32 v25, vcc, 0, v17, vcc
	v_add_co_u32_e32 v26, vcc, 0x3000, v16
	s_nop 1
	v_addc_co_u32_e32 v27, vcc, 0, v17, vcc
	global_load_dword v200, v[16:17], off offset:64
	global_load_dword v201, v[16:17], off offset:2112
	global_load_dword v202, v[18:19], off offset:64
	global_load_dword v203, v[18:19], off offset:2112
	global_load_dword v204, v[24:25], off offset:64
	global_load_dword v205, v[24:25], off offset:2112
	global_load_dword v206, v[26:27], off offset:64
	global_load_dword v207, v[26:27], off offset:2112
	global_load_dword v23, v[16:17], off
	s_nop 0
	global_load_dword v16, v[16:17], off offset:2048
	s_nop 0
	global_load_dword v17, v[18:19], off
	s_nop 0
	global_load_dword v18, v[18:19], off offset:2048
	s_nop 0
	global_load_dword v19, v[24:25], off
	s_nop 0
	global_load_dword v24, v[24:25], off offset:2048
	s_nop 0
	global_load_dword v25, v[26:27], off
	s_nop 0
	global_load_dword v26, v[26:27], off offset:2048
	s_waitcnt vmcnt(0)
	v_cvt_pk_bf16_f32 v16, v23, v16
	v_cvt_pk_bf16_f32 v17, v17, v18
	v_cvt_pk_bf16_f32 v18, v19, v24
	v_cvt_pk_bf16_f32 v19, v25, v26
.LBB0_822:
	s_or_b64 exec, exec, s[0:1]
	s_lshl_b32 s70, s86, 7
	s_or_b32 s60, s70, s78
	s_waitcnt vmcnt(0)
	v_mov_b32_e32 v23, v210
	v_mfma_f32_16x16x32_bf16 v[26:29], v[12:15], v[16:19], 0
	v_add_u32_e32 v24, 0x400, v111
	v_mfma_f32_16x16x32_bf16 v[54:57], v[8:11], v[16:19], 0
	s_nop 5
	v_add_f32_e32 v25, v23, v26
	v_add_f32_e32 v26, v23, v27
	v_min_f32_e32 v51, 0, v25
	v_mul_f32_e64 v25, |v25|, s80
	v_add_f32_e32 v27, v23, v28
	v_min_f32_e32 v53, 0, v26
	v_mul_f32_e64 v26, |v26|, s80
	v_exp_f32_e32 v25, v25
	v_add_f32_e32 v28, v23, v29
	v_add_f32_e32 v29, v23, v54
	v_min_f32_e32 v54, 0, v27
	v_mul_f32_e64 v27, |v27|, s80
	v_exp_f32_e32 v26, v26
	v_add_f32_e32 v49, v23, v55
	v_min_f32_e32 v55, 0, v28
	v_mul_f32_e64 v28, |v28|, s80
	v_exp_f32_e32 v27, v27
	v_exp_f32_e32 v28, v28
	v_add_f32_e32 v25, 1.0, v25
	v_add_f32_e32 v26, 1.0, v26
	v_min_f32_e32 v58, 0, v29
	v_mul_f32_e64 v29, |v29|, s80
	v_add_f32_e32 v27, 1.0, v27
	v_exp_f32_e32 v29, v29
	v_add_f32_e32 v28, 1.0, v28
	v_log_f32_e32 v25, v25
	v_log_f32_e32 v26, v26
	v_log_f32_e32 v27, v27
	v_add_f32_e32 v29, 1.0, v29
	v_log_f32_e32 v28, v28
	v_log_f32_e32 v29, v29
	v_mul_f32_e64 v59, |v49|, s80
	v_exp_f32_e32 v59, v59
	v_fma_f32 v25, -v25, s82, v51
	v_fma_f32 v26, -v26, s82, v53
	v_fma_f32 v27, -v27, s82, v54
	v_fma_f32 v28, -v28, s82, v55
	v_mul_f32_e32 v25, 0x3d800000, v25
	v_mul_f32_e32 v26, 0x3d800000, v26
	v_mul_f32_e32 v27, 0x3d800000, v27
	v_mul_f32_e32 v28, 0x3d800000, v28
	ds_write2_b32 v111, v25, v26 offset1:129
	ds_write2_b32 v24, v27, v28 offset0:2 offset1:131
	v_add_f32_e32 v26, 1.0, v59
	v_log_f32_e32 v26, v26
	v_fma_f32 v25, -v29, s82, v58
	v_add_f32_e32 v29, v23, v56
	v_mul_f32_e32 v27, 0x3d800000, v25
	v_min_f32_e32 v25, 0, v49
	v_mul_f32_e64 v49, |v29|, s80
	v_exp_f32_e32 v49, v49
	s_nop 0
	v_fma_f32 v25, -v26, s82, v25
	v_mul_f32_e32 v26, 0x3d800000, v25
	v_add_f32_e32 v25, 1.0, v49
	v_cmp_gt_f32_e32 vcc, s81, v25
	s_nop 1
	v_cndmask_b32_e64 v28, 0, 32, vcc
	v_ldexp_f32 v25, v25, v28
	v_log_f32_e32 v28, v25
	v_add_u32_e32 v25, 0x2000, v111
	ds_write2_b32 v25, v27, v26 offset0:16 offset1:145
	v_min_f32_e32 v26, 0, v29
	v_add_f32_e32 v29, v23, v57
	v_mul_f32_e32 v27, 0x3f317217, v28
	v_mul_f32_e64 v49, |v29|, s80
	v_fma_f32 v27, v28, s82, -v27
	v_exp_f32_e32 v49, v49
	v_fmac_f32_e32 v27, 0x3377d1cf, v28
	v_fmac_f32_e32 v27, 0x3f317217, v28
	v_cmp_lt_f32_e64 s[0:1], |v28|, s83
	v_min_f32_e32 v51, 0, v29
	s_nop 0
	v_cndmask_b32_e64 v27, v28, v27, s[0:1]
	v_cndmask_b32_e32 v28, 0, v110, vcc
	v_sub_f32_e32 v27, v27, v28
	v_add_f32_e32 v28, 1.0, v49
	v_cmp_gt_f32_e32 vcc, s81, v28
	v_sub_f32_e32 v26, v26, v27
	s_nop 0
	v_cndmask_b32_e64 v49, 0, 32, vcc
	v_ldexp_f32 v28, v28, v49
	v_log_f32_e32 v28, v28
	v_mul_f32_e32 v49, 0x3d800000, v26
	v_cndmask_b32_e32 v54, 0, v110, vcc
	v_mul_f32_e32 v26, 0x3f317217, v28
	v_fma_f32 v26, v28, s82, -v26
	v_fmac_f32_e32 v26, 0x3377d1cf, v28
	v_fmac_f32_e32 v26, 0x3f317217, v28
	v_cmp_lt_f32_e64 s[0:1], |v28|, s83
	s_nop 1
	v_cndmask_b32_e64 v53, v28, v26, s[0:1]
	v_mfma_f32_16x16x32_bf16 v[26:29], v[4:7], v[16:19], 0
	v_sub_f32_e32 v53, v53, v54
	v_sub_f32_e32 v51, v51, v53
	v_mul_f32_e32 v51, 0x3d800000, v51
	v_mfma_f32_16x16x32_bf16 v[16:19], v[0:3], v[16:19], 0
	s_nop 3
	v_add_f32_e32 v55, v23, v26
	v_mul_f32_e64 v26, |v55|, s80
	v_exp_f32_e32 v26, v26
	v_add_f32_e32 v27, v23, v27
	v_mul_f32_e64 v54, |v27|, s80
	v_exp_f32_e32 v54, v54
	v_add_f32_e32 v26, 1.0, v26
	v_cmp_gt_f32_e32 vcc, s81, v26
	v_add_f32_e32 v28, v23, v28
	v_min_f32_e32 v27, 0, v27
	v_cndmask_b32_e64 v53, 0, 32, vcc
	v_ldexp_f32 v26, v26, v53
	v_log_f32_e32 v53, v26
	v_add_u32_e32 v26, 0x2400, v111
	ds_write2_b32 v26, v49, v51 offset0:18 offset1:147
	v_min_f32_e32 v49, 0, v55
	v_mul_f32_e32 v51, 0x3f317217, v53
	v_fma_f32 v51, v53, s82, -v51
	v_fmac_f32_e32 v51, 0x3377d1cf, v53
	v_fmac_f32_e32 v51, 0x3f317217, v53
	v_cmp_lt_f32_e64 s[0:1], |v53|, s83
	v_add_f32_e32 v29, v23, v29
	v_add_f32_e32 v16, v23, v16
	v_cndmask_b32_e64 v51, v53, v51, s[0:1]
	v_cndmask_b32_e32 v53, 0, v110, vcc
	v_sub_f32_e32 v51, v51, v53
	v_add_f32_e32 v53, 1.0, v54
	v_sub_f32_e32 v49, v49, v51
	v_mul_f32_e32 v49, 0x3d800000, v49
	v_log_f32_e32 v53, v53
	v_mul_f32_e64 v54, |v28|, s80
	v_exp_f32_e32 v54, v54
	v_min_f32_e32 v28, 0, v28
	v_add_f32_e32 v17, v23, v17
	v_add_f32_e32 v18, v23, v18
	v_fma_f32 v27, -v53, s82, v27
	v_mul_f32_e32 v51, 0x3d800000, v27
	v_add_f32_e32 v27, 1.0, v54
	s_nop 1
	v_log_f32_e32 v53, v27
	v_add_u32_e32 v27, 0x4000, v111
	ds_write2_b32 v27, v49, v51 offset0:32 offset1:161
	v_mul_f32_e64 v51, |v29|, s80
	v_exp_f32_e32 v51, v51
	s_nop 0
	v_add_f32_e32 v51, 1.0, v51
	s_nop 0
	v_fma_f32 v28, -v53, s82, v28
	v_log_f32_e32 v51, v51
	v_mul_f32_e32 v49, 0x3d800000, v28
	v_min_f32_e32 v28, 0, v29
	v_mul_f32_e64 v53, |v16|, s80
	v_exp_f32_e32 v53, v53
	v_min_f32_e32 v16, 0, v16
	v_fma_f32 v28, -v51, s82, v28
	v_mul_f32_e32 v29, 0x3d800000, v28
	v_add_f32_e32 v28, 1.0, v53
	s_nop 1
	v_log_f32_e32 v51, v28
	v_add_u32_e32 v28, 0x4400, v111
	ds_write2_b32 v28, v49, v29 offset0:34 offset1:163
	v_mul_f32_e64 v49, |v17|, s80
	v_exp_f32_e32 v49, v49
	s_nop 0
	v_add_f32_e32 v49, 1.0, v49
	v_min_f32_e32 v17, 0, v17
	v_fma_f32 v16, -v51, s82, v16
	v_log_f32_e32 v49, v49
	v_mul_f32_e64 v51, |v18|, s80
	v_exp_f32_e32 v51, v51
	v_mul_f32_e32 v16, 0x3d800000, v16
	s_nop 1
	v_fma_f32 v17, -v49, s82, v17
	v_add_f32_e32 v29, 1.0, v51
	v_mul_f32_e32 v17, 0x3d800000, v17
	s_nop 0
	v_log_f32_e32 v49, v29
	v_add_u32_e32 v29, 0x6000, v111
	ds_write2_b32 v29, v16, v17 offset0:48 offset1:177
	v_min_f32_e32 v16, 0, v18
	v_add_f32_e32 v18, v23, v19
	v_mul_f32_e64 v19, |v18|, s80
	v_exp_f32_e32 v19, v19
	s_nop 0
	v_add_f32_e32 v19, 1.0, v19
	v_fma_f32 v16, -v49, s82, v16
	v_log_f32_e32 v19, v19
	v_min_f32_e32 v17, 0, v18
	v_mul_f32_e32 v16, 0x3d800000, v16
	v_add_u32_e32 v49, 0x6400, v111
	s_nop 1
	v_fma_f32 v17, -v19, s82, v17
	v_mul_f32_e32 v17, 0x3d800000, v17
	ds_write2_b32 v49, v16, v17 offset0:50 offset1:179
	v_mov_b32_e32 v16, 0
	v_mov_b32_e32 v17, 0
	v_mov_b32_e32 v18, 0
	v_mov_b32_e32 v19, 0
	s_and_saveexec_b64 s[0:1], s[2:3]
	s_cbranch_execz .LBB0_824
	v_cvt_pk_bf16_f32 v16, v200, v201
	v_cvt_pk_bf16_f32 v17, v202, v203
	v_cvt_pk_bf16_f32 v18, v204, v205
	v_cvt_pk_bf16_f32 v19, v206, v207
.LBB0_824:
	s_or_b64 exec, exec, s[0:1]
	v_add_u32_e32 v20, s60, v34
	v_mov_b32_e32 v21, v31
	v_lshl_add_u64 v[20:21], v[20:21], 2, s[90:91]
	v_mov_b32_e32 v20, v211
	v_mfma_f32_16x16x32_bf16 v[12:15], v[12:15], v[16:19], 0
	v_add_u32_e32 v114, 0x1000, v112
	v_add_u32_e32 v117, 0x1400, v112
	v_add_u32_e32 v120, 0x1800, v112
	v_mfma_f32_16x16x32_bf16 v[8:11], v[8:11], v[16:19], 0
	v_add_u32_e32 v115, 0x1c00, v112
	v_add_u32_e32 v118, 0x2000, v112
	v_add_u32_e32 v121, 0x2400, v112
	v_mfma_f32_16x16x32_bf16 v[4:7], v[4:7], v[16:19], 0
	v_add_u32_e32 v123, 0x2800, v112
	v_add_u32_e32 v124, 0x2c00, v112
	v_add_u32_e32 v122, 0x3000, v112
	v_mfma_f32_16x16x32_bf16 v[0:3], v[0:3], v[16:19], 0
	v_add_u32_e32 v119, 0x3400, v112
	v_add_u32_e32 v116, 0x3800, v112
	v_add_u32_e32 v113, 0x3c00, v112
	s_waitcnt vmcnt(0)
	v_readlane_b32 s98, v244, 4
	s_nop 1
	s_add_i32 s98, s84, s98
	s_cmpk_lt_i32 s98, 0x800
	s_cbranch_scc0 .Lpf_c_skip
	s_lshr_b32 s99, s98, 8
	s_bfe_u32 s100, s98, 0x20006
	s_and_b32 s101, s98, 63
	s_lshl_b32 s98, s99, 2
	s_add_i32 s98, s98, s100
	s_lshl_b32 s98, s98, 7
	s_add_i32 s98, s98, s101
	s_lshl_b32 s98, s98, 15
	v_lshlrev_b32_e32 v246, 6, v145
	v_add_u32_e32 v246, s98, v246
	global_load_dword v240, v246, s[52:53]
	v_add_u32_e32 v246, 0x200000, v246
	global_load_dword v240, v246, s[52:53]
	s_lshl_b32 s99, s99, 12
	s_lshl_b32 s101, s101, 6
	s_add_i32 s99, s99, s101
	s_lshl_b32 s100, s100, 8
	v_add_u32_e32 v245, s99, v144
	v_mul_u32_u24_e32 v245, 0x2600, v245
	v_lshrrev_b32_e32 v246, 6, v145
	v_lshlrev_b32_e32 v247, 6, v246
	v_lshrrev_b32_e32 v246, 2, v246
	v_mul_u32_u24_e32 v246, 0x300, v246
	v_add3_u32 v247, v247, v246, s100
	v_add_u32_e32 v247, v247, v245
	s_add_u32 s98, s54, 0x6800000
	s_addc_u32 s99, s55, 0
	global_load_dword v240, v247, s[98:99] offset:1344
	global_load_dword v240, v247, s[98:99] offset:3392
	v_add_u32_e32 v245, 0x1540, v245
	global_load_dword v240, v245, s[98:99]
